# GQA main loop head aligned to a 64-byte boundary (s_nop padding in the fall-through only)
# speedup vs baseline: 1.0075x; 1.0028x over previous
.LBB0_706:
	s_mul_hi_i32 s0, s14, 0x2aaaaaab
	s_lshr_b32 s1, s0, 31
	s_ashr_i32 s0, s0, 5
	s_add_i32 s0, s0, s1
	s_mul_i32 s1, s0, 0xc0
	s_sub_i32 s1, s14, s1
	s_and_b32 s2, s1, 3
	s_bfe_u32 s4, s1, 0x10002
	s_mul_i32 s2, s2, 24
	s_ashr_i32 s1, s1, 3
	s_add_i32 s5, s2, s1
	s_bfe_i32 s2, s5, 0x80000
	s_bfe_u32 s2, s2, 0x5000a
	s_add_i32 s2, s5, s2
	s_bfe_i32 s2, s2, 0x80000
	s_mul_i32 s1, s4, 3
	s_bfe_u32 s2, s2, 0x80005
	s_add_i32 s6, s1, s2
	s_ashr_i32 s1, s0, 31
	s_lshl_b64 s[2:3], s[0:1], 13
	s_lshl_b32 s1, s5, 8
	s_and_b32 s1, s1, 0x1f00
	s_or_b32 s2, s2, s1
	s_mul_hi_u32 s5, s2, 0xe00
	s_mul_i32 s7, s3, 0xe00
	s_mul_i32 s1, s2, 0xe00
	s_add_i32 s5, s5, s7
	v_readlane_b32 s8, v254, 35
	v_readlane_b32 s9, v254, 36
	s_add_u32 s1, s8, s1
	s_addc_u32 s5, s9, s5
	s_lshl_b32 s16, s6, 6
	s_lshl_b32 s6, s6, 7
	s_add_u32 s1, s1, s6
	s_addc_u32 s5, s5, 0
	s_lshl_b32 s4, s4, 7
	s_add_u32 s6, s10, s4
	s_addc_u32 s7, s11, 0
	v_mov_b32_e32 v42, v191
	s_add_u32 s18, s12, s4
	s_addc_u32 s19, s13, 0
	v_readfirstlane_b32 s17, v42
	s_ashr_i32 s15, s17, 6
	s_lshl_b32 s8, s0, 8
	s_lshl_b32 s36, s15, 5
	s_lshl_b32 s9, s0, 13
	s_add_i32 s20, s8, 0x4000
	v_and_b32_e32 v189, 63, v42
	s_ashr_i32 s37, s36, 31
	s_mul_i32 s0, s15, 0x1c000
	s_mul_hi_i32 s4, s36, 0xe00
	s_add_u32 s22, s1, s0
	v_mul_u32_u24_e32 v0, 0x700, v189
	s_addc_u32 s23, s5, s4
	v_lshlrev_b32_e32 v0, 1, v0
	s_lshl_b32 s0, s15, 3
	v_lshl_add_u64 v[2:3], s[6:7], 0, v[0:1]
	s_ashr_i32 s1, s0, 31
	v_lshl_add_u64 v[192:193], s[0:1], 1, v[2:3]
	s_lshl_b32 s0, s15, 4
	v_bfe_u32 v0, v42, 2, 4
	v_and_or_b32 v0, s0, 48, v0
	v_mul_u32_u24_e32 v0, 0x700, v0
	s_ashr_i32 s0, s17, 3
	v_lshlrev_b32_e32 v0, 1, v0
	s_andn2_b32 s0, s0, 31
	v_lshl_add_u64 v[2:3], s[18:19], 0, v[0:1]
	s_ashr_i32 s1, s0, 31
	v_lshlrev_b32_e32 v198, 3, v42
	s_and_b32 s4, s17, 0x3fffffc0
	v_lshl_add_u64 v[2:3], s[0:1], 1, v[2:3]
	v_and_b32_e32 v201, 24, v198
	s_lshl_b32 s0, s15, 10
	v_lshlrev_b32_e32 v0, 1, v201
	s_cmp_lg_u32 0, -1
	v_lshl_add_u64 v[194:195], v[2:3], 0, v[0:1]
	s_cselect_b32 s1, 0, 0
	v_and_b32_e32 v199, 31, v42
	v_bfe_u32 v200, v42, 5, 1
	s_add_i32 s18, s0, s1
	v_mad_i64_i32 v[2:3], s[0:1], s9, v217, v[192:193]
	s_mov_b32 m0, s18
	s_nop 0
	global_load_lds_dwordx4 v[2:3], off
	s_add_i32 s19, s18, 0x6000
	v_mad_i64_i32 v[82:83], s[0:1], s9, v217, v[194:195]
	s_mov_b32 m0, s19
	s_nop 0
	global_load_lds_dwordx4 v[82:83], off
	s_or_b32 s1, s9, 64
	v_mul_u32_u24_e32 v0, 0x700, v199
	v_lshlrev_b32_e32 v203, 4, v200
	v_mad_i64_i32 v[2:3], s[6:7], s1, v217, v[192:193]
	s_add_i32 s0, s18, 0x2000
	s_mov_b32 m0, s0
	s_nop 0
	global_load_lds_dwordx4 v[2:3], off
	v_lshl_or_b32 v0, v0, 1, v203
	global_load_dwordx4 v[142:145], v0, s[22:23]
	global_load_dwordx4 v[138:141], v0, s[22:23] offset:32
	global_load_dwordx4 v[130:133], v0, s[22:23] offset:64
	global_load_dwordx4 v[122:125], v0, s[22:23] offset:96
	v_lshlrev_b32_e32 v2, 10, v200
	v_lshlrev_b32_e32 v3, 4, v199
	v_add3_u32 v206, 0, v2, v3
	v_mov_b32_e32 v2, v1
	v_mov_b32_e32 v3, v1
	v_mov_b32_e32 v4, v1
	v_mov_b32_e32 v5, v1
	v_mov_b32_e32 v6, v1
	v_mov_b32_e32 v7, v1
	v_mov_b32_e32 v8, v1
	v_mov_b32_e32 v9, v1
	v_mov_b32_e32 v10, v1
	v_mov_b32_e32 v11, v1
	v_mov_b32_e32 v12, v1
	v_mov_b32_e32 v13, v1
	v_mov_b32_e32 v14, v1
	v_mov_b32_e32 v15, v1
	v_mov_b32_e32 v0, v1
	v_mov_b64_e32 v[16:17], v[14:15]
	v_mov_b64_e32 v[14:15], v[12:13]
	v_mov_b64_e32 v[12:13], v[10:11]
	v_mov_b64_e32 v[10:11], v[8:9]
	v_mov_b64_e32 v[8:9], v[6:7]
	v_mov_b64_e32 v[6:7], v[4:5]
	v_mov_b64_e32 v[4:5], v[2:3]
	v_mov_b64_e32 v[2:3], v[0:1]
	s_or_b32 s0, s9, 0x80
	v_mad_i64_i32 v[18:19], s[6:7], s0, v217, v[192:193]
	s_add_i32 s0, s18, 0x4000
	s_mov_b32 m0, s0
	s_nop 0
	global_load_lds_dwordx4 v[18:19], off
	s_waitcnt vmcnt(3) lgkmcnt(0)
	s_barrier
	ds_read_b128 v[34:37], v206
	ds_read_b128 v[38:41], v206 offset:512
	s_waitcnt vmcnt(3) lgkmcnt(1)
	v_mfma_f32_32x32x16_bf16 v[18:33], v[34:37], v[142:145], v[2:17]
	v_lshlrev_b32_e32 v0, 1, v42
	v_and_b32_e32 v202, 32, v0
	v_lshlrev_b32_e32 v0, 4, v42
	s_lshl_b32 s4, s4, 2
	s_add_i32 s17, s4, 0
	s_or_b32 s4, s9, 0xc0
	v_and_b32_e32 v0, 0xc0, v0
	s_waitcnt lgkmcnt(0)
	v_mfma_f32_32x32x16_bf16 v[2:17], v[38:41], v[142:145], v[2:17]
	ds_read_b128 v[34:37], v206 offset:2048
	ds_read_b128 v[38:41], v206 offset:2560
	v_lshl_or_b32 v0, v200, 8, v0
	v_add_u32_e32 v84, 0, v202
	v_mov_b32_e32 v224, 0
	s_movk_i32 s21, 0x4000
	s_mov_b32 s23, -1
	s_mov_b32 s0, 0
	s_waitcnt vmcnt(2) lgkmcnt(1)
	v_mfma_f32_32x32x16_bf16 v[18:33], v[34:37], v[138:141], v[18:33]
	s_movk_i32 s24, 0x2000
	v_add3_u32 v207, v84, v201, v0
	v_cmp_gt_u32_e64 s[40:41], 32, v189
	v_lshl_add_u32 v204, v199, 2, s17
	v_lshl_add_u64 v[196:197], v[82:83], 0, s[28:29]
	s_waitcnt lgkmcnt(0)
	v_mfma_f32_32x32x16_bf16 v[2:17], v[38:41], v[138:141], v[2:17]
	ds_read_b128 v[34:37], v206 offset:4096
	ds_read_b128 v[38:41], v206 offset:4608
	s_waitcnt vmcnt(1) lgkmcnt(1)
	v_mfma_f32_32x32x16_bf16 v[18:33], v[34:37], v[130:133], v[18:33]
	s_waitcnt lgkmcnt(0)
	v_mfma_f32_32x32x16_bf16 v[2:17], v[38:41], v[130:133], v[2:17]
	ds_read_b128 v[34:37], v206 offset:6144
	ds_read_b128 v[38:41], v206 offset:6656
	s_waitcnt vmcnt(0) lgkmcnt(1)
	v_mfma_f32_32x32x16_bf16 v[18:33], v[34:37], v[122:125], v[18:33]
	s_waitcnt lgkmcnt(0)
	v_mfma_f32_32x32x16_bf16 v[2:17], v[38:41], v[122:125], v[2:17]
	s_nop 15
	s_nop 7
	s_nop 0
	v_max3_f32 v34, v18, v19, v2
	v_max3_f32 v35, v20, v21, v3
	s_nop 0
	v_max3_f32 v34, v34, v4, v5
	v_max3_f32 v35, v35, v24, v25
	s_nop 0
	v_max3_f32 v34, v34, v22, v23
	v_max3_f32 v35, v35, v8, v9
	s_nop 0
	v_max3_f32 v34, v34, v6, v7
	v_max3_f32 v35, v35, v28, v29
	s_nop 0
	v_max3_f32 v34, v34, v26, v27
	v_max3_f32 v35, v35, v12, v13
	s_nop 0
	v_max3_f32 v34, v34, v10, v11
	v_max3_f32 v35, v35, v32, v33
	s_nop 0
	v_max3_f32 v34, v34, v30, v31
	v_max3_f32 v35, v35, v16, v17
	s_nop 0
	v_max3_f32 v34, v34, v14, v15
	s_nop 0
	v_max_f32_e32 v34, v34, v35
	s_nop 0
	v_mov_b32_e32 v35, v34
	s_nop 1
	v_permlane32_swap_b32_e32 v34, v35
	v_max_f32_e32 v34, v34, v35
	s_nop 0
	v_add_f32_e32 v205, v1, v34
	v_sub_f32_e32 v18, v18, v34
	v_sub_f32_e32 v2, v2, v34
	v_sub_f32_e32 v19, v19, v34
	v_sub_f32_e32 v3, v3, v34
	v_sub_f32_e32 v20, v20, v34
	v_sub_f32_e32 v4, v4, v34
	v_sub_f32_e32 v21, v21, v34
	v_sub_f32_e32 v5, v5, v34
	v_sub_f32_e32 v22, v22, v34
	v_sub_f32_e32 v6, v6, v34
	v_sub_f32_e32 v23, v23, v34
	v_sub_f32_e32 v7, v7, v34
	v_sub_f32_e32 v24, v24, v34
	v_sub_f32_e32 v8, v8, v34
	v_sub_f32_e32 v25, v25, v34
	v_sub_f32_e32 v9, v9, v34
	v_sub_f32_e32 v26, v26, v34
	v_sub_f32_e32 v10, v10, v34
	v_sub_f32_e32 v27, v27, v34
	v_sub_f32_e32 v11, v11, v34
	v_sub_f32_e32 v28, v28, v34
	v_sub_f32_e32 v12, v12, v34
	v_sub_f32_e32 v29, v29, v34
	v_sub_f32_e32 v13, v13, v34
	v_sub_f32_e32 v30, v30, v34
	v_sub_f32_e32 v14, v14, v34
	v_sub_f32_e32 v31, v31, v34
	v_sub_f32_e32 v15, v15, v34
	v_sub_f32_e32 v32, v32, v34
	v_sub_f32_e32 v16, v16, v34
	v_sub_f32_e32 v33, v33, v34
	v_sub_f32_e32 v17, v17, v34
	s_nop 0
	v_xor_b32_e32 v34, 0x80000000, v205
	v_mov_b32_e32 v35, v34
	v_mov_b32_e32 v36, v34
	v_mov_b32_e32 v37, v34
	v_mov_b32_e32 v38, v34
	v_mov_b32_e32 v39, v34
	v_mov_b32_e32 v40, v34
	v_mov_b32_e32 v41, v34
	v_mov_b32_e32 v42, v34
	v_mov_b32_e32 v43, v34
	v_mov_b32_e32 v44, v34
	v_mov_b32_e32 v45, v34
	v_mov_b32_e32 v46, v34
	v_mov_b32_e32 v47, v34
	v_mov_b32_e32 v48, v34
	v_mov_b32_e32 v49, v34
	s_waitcnt vmcnt(0) lgkmcnt(0)
	s_barrier
	v_exp_f32_e32 v50, v2
	v_exp_f32_e32 v51, v3
	v_mad_i64_i32 v[2:3], s[4:5], s4, v217, v[192:193]
	s_mov_b32 m0, s18
	s_nop 0
	global_load_lds_dwordx4 v[2:3], off
	v_exp_f32_e32 v66, v18
	v_mad_i64_i32 v[2:3], s[4:5], s1, v217, v[194:195]
	s_add_i32 s1, s18, 0x8000
	s_mov_b32 m0, s1
	s_nop 0
	global_load_lds_dwordx4 v[2:3], off
	ds_read_b128 v[174:177], v206 offset:8192
	ds_read_b128 v[170:173], v206 offset:8704
	ds_read_b128 v[166:169], v206 offset:10240
	ds_read_b128 v[162:165], v206 offset:10752
	ds_read_b128 v[158:161], v206 offset:12288
	ds_read_b128 v[154:157], v206 offset:12800
	ds_read_b128 v[150:153], v206 offset:14336
	ds_read_b128 v[146:149], v206 offset:14848
	v_exp_f32_e32 v67, v19
	v_exp_f32_e32 v68, v20
	v_exp_f32_e32 v69, v21
	v_exp_f32_e32 v70, v22
	v_exp_f32_e32 v71, v23
	v_exp_f32_e32 v72, v24
	v_exp_f32_e32 v73, v25
	v_exp_f32_e32 v74, v26
	v_exp_f32_e32 v75, v27
	v_exp_f32_e32 v76, v28
	v_exp_f32_e32 v77, v29
	v_exp_f32_e32 v78, v30
	v_exp_f32_e32 v79, v31
	v_exp_f32_e32 v80, v32
	v_exp_f32_e32 v81, v33
	v_exp_f32_e32 v52, v4
	v_exp_f32_e32 v53, v5
	v_exp_f32_e32 v54, v6
	v_exp_f32_e32 v55, v7
	v_exp_f32_e32 v56, v8
	v_exp_f32_e32 v57, v9
	v_exp_f32_e32 v58, v10
	v_exp_f32_e32 v59, v11
	v_exp_f32_e32 v60, v12
	v_exp_f32_e32 v61, v13
	v_exp_f32_e32 v62, v14
	v_exp_f32_e32 v63, v15
	v_exp_f32_e32 v64, v16
	v_exp_f32_e32 v65, v17
	s_waitcnt vmcnt(2) lgkmcnt(0)
	s_barrier
	v_mov_b32_e32 v2, 0
	v_mov_b32_e32 v3, v224
	v_mov_b32_e32 v4, v224
	v_mov_b32_e32 v5, v224
	v_mov_b32_e32 v6, v224
	v_mov_b32_e32 v7, v224
	v_mov_b32_e32 v8, v224
	v_mov_b32_e32 v9, v224
	v_mov_b32_e32 v10, v224
	v_mov_b32_e32 v11, v224
	v_mov_b32_e32 v12, v224
	v_mov_b32_e32 v13, v224
	v_mov_b32_e32 v14, v224
	v_mov_b32_e32 v15, v224
	v_mov_b32_e32 v16, v224
	v_mov_b32_e32 v17, v224
	v_mov_b32_e32 v18, 0
	v_mov_b32_e32 v19, v224
	v_mov_b32_e32 v20, v224
	v_mov_b32_e32 v21, v224
	v_mov_b32_e32 v22, v224
	v_mov_b32_e32 v23, v224
	v_mov_b32_e32 v24, v224
	v_mov_b32_e32 v25, v224
	v_mov_b32_e32 v26, v224
	v_mov_b32_e32 v27, v224
	v_mov_b32_e32 v28, v224
	v_mov_b32_e32 v29, v224
	v_mov_b32_e32 v30, v224
	v_mov_b32_e32 v31, v224
	v_mov_b32_e32 v32, v224
	v_mov_b32_e32 v33, v224
	.p2alignl 6, 3212836864
